# FFN1 epilogue paired stores: mixlo/mixhi pack + DPP lane exchange + v_perm, 32 dword stores per thread instead of 64 short stores
# speedup vs baseline: 1.0016x; 1.0016x over previous
; DI int TIDX() { int t = threadIdx.x; asm volatile("" : "+v"(t)); return t; }
; DI float sigmoidf_(float x) { return __builtin_amdgcn_rcpf(1.f + __expf(-x)); }
; DI void phase_ffn1(const P& p, int l, int hf, char* smem) {
;     ...
;     const int lane = TIDX() & 63, w = TIDX() >> 6, wm = w >> 1, wn = w & 1, hh = lane >> 5, c = lane & 31;
;     const int ml0 = m0 - mt0 * 128;
; #pragma unroll
;     for (int mi = 0; mi < 4; ++mi) {
;       const int rbase = ml0 + wm * 128 + mi * 32 + 4 * hh, n = c0 + wn * 32 + c;
; #pragma unroll
;       for (int i = 0; i < 16; ++i) {
;         const float g = acc[mi][0][i];
;         act[(size_t)EROW(rbase, i) * 2816 + n] = (h16)(g * sigmoidf_(g) * acc[mi][1][i]);
;       }
;     }
.LBB0_69:
	v_mov_b32_e32 v0, v203
	v_mov_b32_e32 v130, v203
	s_barrier
	s_movk_i32 s2, 0x1600
	v_and_b32_e32 v132, 0xffffff80, v203
	v_add_u32_e32 v132, s12, v132
	v_lshrrev_b32_e32 v133, 3, v203
	v_and_or_b32 v132, v133, 4, v132
	v_and_b32_e32 v131, 31, v203
	v_lshrrev_b32_e32 v130, 1, v203
	v_and_b32_e32 v130, 32, v130
	v_or3_b32 v130, v131, v130, s26
	v_and_b32_e32 v133, 1, v130
	v_add_u32_e32 v132, v132, v133
	v_and_b32_e32 v130, -2, v130
	v_lshlrev_b32_e32 v130, 1, v130
	v_mad_u32_u24 v130, v132, s2, v130
	v_mov_b32_e32 v194, 0x05040100
	v_mov_b32_e32 v131, 0x03020706
	v_cmp_eq_u32_e64 s[12:13], 1, v133
	s_nop 1
	v_cndmask_b32_e64 v194, v194, v131, s[12:13]
	v_mul_f32_e32 v178, 0xbfb8aa3b, v114
	v_mul_f32_e32 v179, 0xbfb8aa3b, v115
	v_mul_f32_e32 v180, 0xbfb8aa3b, v116
	v_mul_f32_e32 v181, 0xbfb8aa3b, v117
	v_mul_f32_e32 v182, 0xbfb8aa3b, v118
	v_mul_f32_e32 v183, 0xbfb8aa3b, v119
	v_mul_f32_e32 v184, 0xbfb8aa3b, v120
	v_mul_f32_e32 v185, 0xbfb8aa3b, v121
	v_exp_f32_e32 v178, v178
	v_exp_f32_e32 v179, v179
	v_exp_f32_e32 v180, v180
	v_exp_f32_e32 v181, v181
	v_exp_f32_e32 v182, v182
	v_exp_f32_e32 v183, v183
	v_exp_f32_e32 v184, v184
	v_exp_f32_e32 v185, v185
	v_mov_b32_e32 v190, v130
	v_add_u32_e32 v191, 0x2c00, v130
	v_add_u32_e32 v192, 0xb000, v130
	v_add_u32_e32 v193, 0xdc00, v130
	v_add_f32_e32 v178, 1.0, v178
	v_add_f32_e32 v179, 1.0, v179
	v_add_f32_e32 v180, 1.0, v180
	v_add_f32_e32 v181, 1.0, v181
	v_add_f32_e32 v182, 1.0, v182
	v_add_f32_e32 v183, 1.0, v183
	v_add_f32_e32 v184, 1.0, v184
	v_add_f32_e32 v185, 1.0, v185
	v_rcp_f32_e32 v178, v178
	v_rcp_f32_e32 v179, v179
	v_rcp_f32_e32 v180, v180
	v_rcp_f32_e32 v181, v181
	v_rcp_f32_e32 v182, v182
	v_rcp_f32_e32 v183, v183
	v_rcp_f32_e32 v184, v184
	v_rcp_f32_e32 v185, v185
	v_mul_f32_e32 v178, v114, v178
	v_mul_f32_e32 v179, v115, v179
	v_mul_f32_e32 v180, v116, v180
	v_mul_f32_e32 v181, v117, v181
	v_mul_f32_e32 v182, v118, v182
	v_mul_f32_e32 v183, v119, v183
	v_mul_f32_e32 v184, v120, v184
	v_mul_f32_e32 v185, v121, v185
	v_fma_mixlo_f16 v178, v98, v178, 0
	v_fma_mixlo_f16 v180, v100, v180, 0
	v_fma_mixlo_f16 v182, v102, v182, 0
	v_fma_mixlo_f16 v184, v104, v184, 0
	v_fma_mixhi_f16 v178, v99, v179, 0
	v_fma_mixhi_f16 v180, v101, v181, 0
	v_fma_mixhi_f16 v182, v103, v183, 0
	v_fma_mixhi_f16 v184, v105, v185, 0
	v_mov_b32_dpp v186, v178 quad_perm:[1,0,3,2] row_mask:0xf bank_mask:0xf
	v_mov_b32_dpp v187, v180 quad_perm:[1,0,3,2] row_mask:0xf bank_mask:0xf
	v_mov_b32_dpp v188, v182 quad_perm:[1,0,3,2] row_mask:0xf bank_mask:0xf
	v_mov_b32_dpp v189, v184 quad_perm:[1,0,3,2] row_mask:0xf bank_mask:0xf
	v_perm_b32 v178, v186, v178, v194
	v_perm_b32 v180, v187, v180, v194
	v_perm_b32 v182, v188, v182, v194
	v_perm_b32 v184, v189, v184, v194
	global_store_dword v190, v178, s[8:9]
	global_store_dword v191, v180, s[8:9]
	global_store_dword v192, v182, s[8:9]
	global_store_dword v193, v184, s[8:9]
	v_mul_f32_e32 v178, 0xbfb8aa3b, v122
	v_mul_f32_e32 v179, 0xbfb8aa3b, v123
	v_mul_f32_e32 v180, 0xbfb8aa3b, v124
	v_mul_f32_e32 v181, 0xbfb8aa3b, v125
	v_mul_f32_e32 v182, 0xbfb8aa3b, v126
	v_mul_f32_e32 v183, 0xbfb8aa3b, v127
	v_mul_f32_e32 v184, 0xbfb8aa3b, v128
	v_mul_f32_e32 v185, 0xbfb8aa3b, v129
	v_exp_f32_e32 v178, v178
	v_exp_f32_e32 v179, v179
	v_exp_f32_e32 v180, v180
	v_exp_f32_e32 v181, v181
	v_exp_f32_e32 v182, v182
	v_exp_f32_e32 v183, v183
	v_exp_f32_e32 v184, v184
	v_exp_f32_e32 v185, v185
	v_add_u32_e32 v190, 0x16000, v130
	v_add_u32_e32 v191, 0x18c00, v130
	v_add_u32_e32 v192, 0x21000, v130
	v_add_u32_e32 v193, 0x23c00, v130
	v_add_f32_e32 v178, 1.0, v178
	v_add_f32_e32 v179, 1.0, v179
	v_add_f32_e32 v180, 1.0, v180
	v_add_f32_e32 v181, 1.0, v181
	v_add_f32_e32 v182, 1.0, v182
	v_add_f32_e32 v183, 1.0, v183
	v_add_f32_e32 v184, 1.0, v184
	v_add_f32_e32 v185, 1.0, v185
	v_rcp_f32_e32 v178, v178
	v_rcp_f32_e32 v179, v179
	v_rcp_f32_e32 v180, v180
	v_rcp_f32_e32 v181, v181
	v_rcp_f32_e32 v182, v182
	v_rcp_f32_e32 v183, v183
	v_rcp_f32_e32 v184, v184
	v_rcp_f32_e32 v185, v185
	v_mul_f32_e32 v178, v122, v178
	v_mul_f32_e32 v179, v123, v179
	v_mul_f32_e32 v180, v124, v180
	v_mul_f32_e32 v181, v125, v181
	v_mul_f32_e32 v182, v126, v182
	v_mul_f32_e32 v183, v127, v183
	v_mul_f32_e32 v184, v128, v184
	v_mul_f32_e32 v185, v129, v185
	v_fma_mixlo_f16 v178, v106, v178, 0
	v_fma_mixlo_f16 v180, v108, v180, 0
	v_fma_mixlo_f16 v182, v110, v182, 0
	v_fma_mixlo_f16 v184, v112, v184, 0
	v_fma_mixhi_f16 v178, v107, v179, 0
	v_fma_mixhi_f16 v180, v109, v181, 0
	v_fma_mixhi_f16 v182, v111, v183, 0
	v_fma_mixhi_f16 v184, v113, v185, 0
	v_mov_b32_dpp v186, v178 quad_perm:[1,0,3,2] row_mask:0xf bank_mask:0xf
	v_mov_b32_dpp v187, v180 quad_perm:[1,0,3,2] row_mask:0xf bank_mask:0xf
	v_mov_b32_dpp v188, v182 quad_perm:[1,0,3,2] row_mask:0xf bank_mask:0xf
	v_mov_b32_dpp v189, v184 quad_perm:[1,0,3,2] row_mask:0xf bank_mask:0xf
	v_perm_b32 v178, v186, v178, v194
	v_perm_b32 v180, v187, v180, v194
	v_perm_b32 v182, v188, v182, v194
	v_perm_b32 v184, v189, v184, v194
	global_store_dword v190, v178, s[8:9]
	global_store_dword v191, v180, s[8:9]
	global_store_dword v192, v182, s[8:9]
	global_store_dword v193, v184, s[8:9]
	v_mul_f32_e32 v178, 0xbfb8aa3b, v82
	v_mul_f32_e32 v179, 0xbfb8aa3b, v83
	v_mul_f32_e32 v180, 0xbfb8aa3b, v84
	v_mul_f32_e32 v181, 0xbfb8aa3b, v85
	v_mul_f32_e32 v182, 0xbfb8aa3b, v86
	v_mul_f32_e32 v183, 0xbfb8aa3b, v87
	v_mul_f32_e32 v184, 0xbfb8aa3b, v88
	v_mul_f32_e32 v185, 0xbfb8aa3b, v89
	v_exp_f32_e32 v178, v178
	v_exp_f32_e32 v179, v179
	v_exp_f32_e32 v180, v180
	v_exp_f32_e32 v181, v181
	v_exp_f32_e32 v182, v182
	v_exp_f32_e32 v183, v183
	v_exp_f32_e32 v184, v184
; DI int TIDX() { int t = threadIdx.x; asm volatile("" : "+v"(t)); return t; }
; DI float sigmoidf_(float x) { return __builtin_amdgcn_rcpf(1.f + __expf(-x)); }
; DI void phase_ffn1(const P& p, int l, int hf, char* smem) {
;     ...
;     const int lane = TIDX() & 63, w = TIDX() >> 6, wm = w >> 1, wn = w & 1, hh = lane >> 5, c = lane & 31;
;     const int ml0 = m0 - mt0 * 128;
; #pragma unroll
;     for (int mi = 0; mi < 4; ++mi) {
;       const int rbase = ml0 + wm * 128 + mi * 32 + 4 * hh, n = c0 + wn * 32 + c;
; #pragma unroll
;       for (int i = 0; i < 16; ++i) {
;         const float g = acc[mi][0][i];
;         act[(size_t)EROW(rbase, i) * 2816 + n] = (h16)(g * sigmoidf_(g) * acc[mi][1][i]);
;       }
;     }
	v_exp_f32_e32 v185, v185
	v_add_u32_e32 v190, 0x2c000, v130
	v_add_u32_e32 v191, 0x2ec00, v130
	v_add_u32_e32 v192, 0x37000, v130
	v_add_u32_e32 v193, 0x39c00, v130
	v_add_f32_e32 v178, 1.0, v178
	v_add_f32_e32 v179, 1.0, v179
	v_add_f32_e32 v180, 1.0, v180
	v_add_f32_e32 v181, 1.0, v181
	v_add_f32_e32 v182, 1.0, v182
	v_add_f32_e32 v183, 1.0, v183
	v_add_f32_e32 v184, 1.0, v184
	v_add_f32_e32 v185, 1.0, v185
	v_rcp_f32_e32 v178, v178
	v_rcp_f32_e32 v179, v179
	v_rcp_f32_e32 v180, v180
	v_rcp_f32_e32 v181, v181
	v_rcp_f32_e32 v182, v182
	v_rcp_f32_e32 v183, v183
	v_rcp_f32_e32 v184, v184
	v_rcp_f32_e32 v185, v185
	v_mul_f32_e32 v178, v82, v178
	v_mul_f32_e32 v179, v83, v179
	v_mul_f32_e32 v180, v84, v180
	v_mul_f32_e32 v181, v85, v181
	v_mul_f32_e32 v182, v86, v182
	v_mul_f32_e32 v183, v87, v183
	v_mul_f32_e32 v184, v88, v184
	v_mul_f32_e32 v185, v89, v185
	v_fma_mixlo_f16 v178, v66, v178, 0
	v_fma_mixlo_f16 v180, v68, v180, 0
	v_fma_mixlo_f16 v182, v70, v182, 0
	v_fma_mixlo_f16 v184, v72, v184, 0
	v_fma_mixhi_f16 v178, v67, v179, 0
	v_fma_mixhi_f16 v180, v69, v181, 0
	v_fma_mixhi_f16 v182, v71, v183, 0
	v_fma_mixhi_f16 v184, v73, v185, 0
	v_mov_b32_dpp v186, v178 quad_perm:[1,0,3,2] row_mask:0xf bank_mask:0xf
	v_mov_b32_dpp v187, v180 quad_perm:[1,0,3,2] row_mask:0xf bank_mask:0xf
	v_mov_b32_dpp v188, v182 quad_perm:[1,0,3,2] row_mask:0xf bank_mask:0xf
	v_mov_b32_dpp v189, v184 quad_perm:[1,0,3,2] row_mask:0xf bank_mask:0xf
	v_perm_b32 v178, v186, v178, v194
	v_perm_b32 v180, v187, v180, v194
	v_perm_b32 v182, v188, v182, v194
	v_perm_b32 v184, v189, v184, v194
	global_store_dword v190, v178, s[8:9]
	global_store_dword v191, v180, s[8:9]
	global_store_dword v192, v182, s[8:9]
	global_store_dword v193, v184, s[8:9]
	v_mul_f32_e32 v178, 0xbfb8aa3b, v90
	v_mul_f32_e32 v179, 0xbfb8aa3b, v91
	v_mul_f32_e32 v180, 0xbfb8aa3b, v92
	v_mul_f32_e32 v181, 0xbfb8aa3b, v93
	v_mul_f32_e32 v182, 0xbfb8aa3b, v94
	v_mul_f32_e32 v183, 0xbfb8aa3b, v95
	v_mul_f32_e32 v184, 0xbfb8aa3b, v96
	v_mul_f32_e32 v185, 0xbfb8aa3b, v97
	v_exp_f32_e32 v178, v178
	v_exp_f32_e32 v179, v179
	v_exp_f32_e32 v180, v180
	v_exp_f32_e32 v181, v181
	v_exp_f32_e32 v182, v182
	v_exp_f32_e32 v183, v183
	v_exp_f32_e32 v184, v184
	v_exp_f32_e32 v185, v185
	v_add_u32_e32 v190, 0x42000, v130
	v_add_u32_e32 v191, 0x44c00, v130
	v_add_u32_e32 v192, 0x4d000, v130
	v_add_u32_e32 v193, 0x4fc00, v130
	v_add_f32_e32 v178, 1.0, v178
	v_add_f32_e32 v179, 1.0, v179
	v_add_f32_e32 v180, 1.0, v180
	v_add_f32_e32 v181, 1.0, v181
	v_add_f32_e32 v182, 1.0, v182
	v_add_f32_e32 v183, 1.0, v183
	v_add_f32_e32 v184, 1.0, v184
	v_add_f32_e32 v185, 1.0, v185
	v_rcp_f32_e32 v178, v178
	v_rcp_f32_e32 v179, v179
	v_rcp_f32_e32 v180, v180
	v_rcp_f32_e32 v181, v181
	v_rcp_f32_e32 v182, v182
	v_rcp_f32_e32 v183, v183
	v_rcp_f32_e32 v184, v184
	v_rcp_f32_e32 v185, v185
	v_mul_f32_e32 v178, v90, v178
	v_mul_f32_e32 v179, v91, v179
	v_mul_f32_e32 v180, v92, v180
	v_mul_f32_e32 v181, v93, v181
	v_mul_f32_e32 v182, v94, v182
	v_mul_f32_e32 v183, v95, v183
	v_mul_f32_e32 v184, v96, v184
	v_mul_f32_e32 v185, v97, v185
	v_fma_mixlo_f16 v178, v74, v178, 0
	v_fma_mixlo_f16 v180, v76, v180, 0
	v_fma_mixlo_f16 v182, v78, v182, 0
	v_fma_mixlo_f16 v184, v80, v184, 0
	v_fma_mixhi_f16 v178, v75, v179, 0
	v_fma_mixhi_f16 v180, v77, v181, 0
	v_fma_mixhi_f16 v182, v79, v183, 0
	v_fma_mixhi_f16 v184, v81, v185, 0
	v_mov_b32_dpp v186, v178 quad_perm:[1,0,3,2] row_mask:0xf bank_mask:0xf
	v_mov_b32_dpp v187, v180 quad_perm:[1,0,3,2] row_mask:0xf bank_mask:0xf
	v_mov_b32_dpp v188, v182 quad_perm:[1,0,3,2] row_mask:0xf bank_mask:0xf
	v_mov_b32_dpp v189, v184 quad_perm:[1,0,3,2] row_mask:0xf bank_mask:0xf
	v_perm_b32 v178, v186, v178, v194
	v_perm_b32 v180, v187, v180, v194
	v_perm_b32 v182, v188, v182, v194
	v_perm_b32 v184, v189, v184, v194
	global_store_dword v190, v178, s[8:9]
	global_store_dword v191, v180, s[8:9]
	global_store_dword v192, v182, s[8:9]
	global_store_dword v193, v184, s[8:9]
	v_mul_f32_e32 v178, 0xbfb8aa3b, v50
	v_mul_f32_e32 v179, 0xbfb8aa3b, v51
	v_mul_f32_e32 v180, 0xbfb8aa3b, v52
	v_mul_f32_e32 v181, 0xbfb8aa3b, v53
	v_mul_f32_e32 v182, 0xbfb8aa3b, v54
	v_mul_f32_e32 v183, 0xbfb8aa3b, v55
	v_mul_f32_e32 v184, 0xbfb8aa3b, v56
	v_mul_f32_e32 v185, 0xbfb8aa3b, v57
	v_exp_f32_e32 v178, v178
	v_exp_f32_e32 v179, v179
	v_exp_f32_e32 v180, v180
	v_exp_f32_e32 v181, v181
	v_exp_f32_e32 v182, v182
	v_exp_f32_e32 v183, v183
	v_exp_f32_e32 v184, v184
	v_exp_f32_e32 v185, v185
	v_add_u32_e32 v190, 0x58000, v130
	v_add_u32_e32 v191, 0x5ac00, v130
	v_add_u32_e32 v192, 0x63000, v130
	v_add_u32_e32 v193, 0x65c00, v130
	v_add_f32_e32 v178, 1.0, v178
	v_add_f32_e32 v179, 1.0, v179
	v_add_f32_e32 v180, 1.0, v180
	v_add_f32_e32 v181, 1.0, v181
	v_add_f32_e32 v182, 1.0, v182
	v_add_f32_e32 v183, 1.0, v183
	v_add_f32_e32 v184, 1.0, v184
	v_add_f32_e32 v185, 1.0, v185
	v_rcp_f32_e32 v178, v178
	v_rcp_f32_e32 v179, v179
	v_rcp_f32_e32 v180, v180
	v_rcp_f32_e32 v181, v181
	v_rcp_f32_e32 v182, v182
	v_rcp_f32_e32 v183, v183
	v_rcp_f32_e32 v184, v184
	v_rcp_f32_e32 v185, v185
	v_mul_f32_e32 v178, v50, v178
	v_mul_f32_e32 v179, v51, v179
	v_mul_f32_e32 v180, v52, v180
	v_mul_f32_e32 v181, v53, v181
	v_mul_f32_e32 v182, v54, v182
	v_mul_f32_e32 v183, v55, v183
	v_mul_f32_e32 v184, v56, v184
	v_mul_f32_e32 v185, v57, v185
	v_fma_mixlo_f16 v178, v34, v178, 0
	v_fma_mixlo_f16 v180, v36, v180, 0
	v_fma_mixlo_f16 v182, v38, v182, 0
	v_fma_mixlo_f16 v184, v40, v184, 0
	v_fma_mixhi_f16 v178, v35, v179, 0
	v_fma_mixhi_f16 v180, v37, v181, 0
	v_fma_mixhi_f16 v182, v39, v183, 0
	v_fma_mixhi_f16 v184, v41, v185, 0
; DI int TIDX() { int t = threadIdx.x; asm volatile("" : "+v"(t)); return t; }
; DI float sigmoidf_(float x) { return __builtin_amdgcn_rcpf(1.f + __expf(-x)); }
; DI void phase_ffn1(const P& p, int l, int hf, char* smem) {
;     ...
;     const int lane = TIDX() & 63, w = TIDX() >> 6, wm = w >> 1, wn = w & 1, hh = lane >> 5, c = lane & 31;
;     const int ml0 = m0 - mt0 * 128;
; #pragma unroll
;     for (int mi = 0; mi < 4; ++mi) {
;       const int rbase = ml0 + wm * 128 + mi * 32 + 4 * hh, n = c0 + wn * 32 + c;
; #pragma unroll
;       for (int i = 0; i < 16; ++i) {
;         const float g = acc[mi][0][i];
;         act[(size_t)EROW(rbase, i) * 2816 + n] = (h16)(g * sigmoidf_(g) * acc[mi][1][i]);
;       }
;     }
	v_mov_b32_dpp v186, v178 quad_perm:[1,0,3,2] row_mask:0xf bank_mask:0xf
	v_mov_b32_dpp v187, v180 quad_perm:[1,0,3,2] row_mask:0xf bank_mask:0xf
	v_mov_b32_dpp v188, v182 quad_perm:[1,0,3,2] row_mask:0xf bank_mask:0xf
	v_mov_b32_dpp v189, v184 quad_perm:[1,0,3,2] row_mask:0xf bank_mask:0xf
	v_perm_b32 v178, v186, v178, v194
	v_perm_b32 v180, v187, v180, v194
	v_perm_b32 v182, v188, v182, v194
	v_perm_b32 v184, v189, v184, v194
	global_store_dword v190, v178, s[8:9]
	global_store_dword v191, v180, s[8:9]
	global_store_dword v192, v182, s[8:9]
	global_store_dword v193, v184, s[8:9]
	v_mul_f32_e32 v178, 0xbfb8aa3b, v58
	v_mul_f32_e32 v179, 0xbfb8aa3b, v59
	v_mul_f32_e32 v180, 0xbfb8aa3b, v60
	v_mul_f32_e32 v181, 0xbfb8aa3b, v61
	v_mul_f32_e32 v182, 0xbfb8aa3b, v62
	v_mul_f32_e32 v183, 0xbfb8aa3b, v63
	v_mul_f32_e32 v184, 0xbfb8aa3b, v64
	v_mul_f32_e32 v185, 0xbfb8aa3b, v65
	v_exp_f32_e32 v178, v178
	v_exp_f32_e32 v179, v179
	v_exp_f32_e32 v180, v180
	v_exp_f32_e32 v181, v181
	v_exp_f32_e32 v182, v182
	v_exp_f32_e32 v183, v183
	v_exp_f32_e32 v184, v184
	v_exp_f32_e32 v185, v185
	v_add_u32_e32 v190, 0x6e000, v130
	v_add_u32_e32 v191, 0x70c00, v130
	v_add_u32_e32 v192, 0x79000, v130
	v_add_u32_e32 v193, 0x7bc00, v130
	v_add_f32_e32 v178, 1.0, v178
	v_add_f32_e32 v179, 1.0, v179
	v_add_f32_e32 v180, 1.0, v180
	v_add_f32_e32 v181, 1.0, v181
	v_add_f32_e32 v182, 1.0, v182
	v_add_f32_e32 v183, 1.0, v183
	v_add_f32_e32 v184, 1.0, v184
	v_add_f32_e32 v185, 1.0, v185
	v_rcp_f32_e32 v178, v178
	v_rcp_f32_e32 v179, v179
	v_rcp_f32_e32 v180, v180
	v_rcp_f32_e32 v181, v181
	v_rcp_f32_e32 v182, v182
	v_rcp_f32_e32 v183, v183
	v_rcp_f32_e32 v184, v184
	v_rcp_f32_e32 v185, v185
	v_mul_f32_e32 v178, v58, v178
	v_mul_f32_e32 v179, v59, v179
	v_mul_f32_e32 v180, v60, v180
	v_mul_f32_e32 v181, v61, v181
	v_mul_f32_e32 v182, v62, v182
	v_mul_f32_e32 v183, v63, v183
	v_mul_f32_e32 v184, v64, v184
	v_mul_f32_e32 v185, v65, v185
	v_fma_mixlo_f16 v178, v42, v178, 0
	v_fma_mixlo_f16 v180, v44, v180, 0
	v_fma_mixlo_f16 v182, v46, v182, 0
	v_fma_mixlo_f16 v184, v48, v184, 0
	v_fma_mixhi_f16 v178, v43, v179, 0
	v_fma_mixhi_f16 v180, v45, v181, 0
	v_fma_mixhi_f16 v182, v47, v183, 0
	v_fma_mixhi_f16 v184, v49, v185, 0
	v_mov_b32_dpp v186, v178 quad_perm:[1,0,3,2] row_mask:0xf bank_mask:0xf
	v_mov_b32_dpp v187, v180 quad_perm:[1,0,3,2] row_mask:0xf bank_mask:0xf
	v_mov_b32_dpp v188, v182 quad_perm:[1,0,3,2] row_mask:0xf bank_mask:0xf
	v_mov_b32_dpp v189, v184 quad_perm:[1,0,3,2] row_mask:0xf bank_mask:0xf
	v_perm_b32 v178, v186, v178, v194
	v_perm_b32 v180, v187, v180, v194
	v_perm_b32 v182, v188, v182, v194
	v_perm_b32 v184, v189, v184, v194
	global_store_dword v190, v178, s[8:9]
	global_store_dword v191, v180, s[8:9]
	global_store_dword v192, v182, s[8:9]
	global_store_dword v193, v184, s[8:9]
	v_mul_f32_e32 v178, 0xbfb8aa3b, v18
	v_mul_f32_e32 v179, 0xbfb8aa3b, v19
	v_mul_f32_e32 v180, 0xbfb8aa3b, v20
	v_mul_f32_e32 v181, 0xbfb8aa3b, v21
	v_mul_f32_e32 v182, 0xbfb8aa3b, v22
	v_mul_f32_e32 v183, 0xbfb8aa3b, v23
	v_mul_f32_e32 v184, 0xbfb8aa3b, v24
	v_mul_f32_e32 v185, 0xbfb8aa3b, v25
	v_exp_f32_e32 v178, v178
	v_exp_f32_e32 v179, v179
	v_exp_f32_e32 v180, v180
	v_exp_f32_e32 v181, v181
	v_exp_f32_e32 v182, v182
	v_exp_f32_e32 v183, v183
	v_exp_f32_e32 v184, v184
	v_exp_f32_e32 v185, v185
	v_add_u32_e32 v190, 0x84000, v130
	v_add_u32_e32 v191, 0x86c00, v130
	v_add_u32_e32 v192, 0x8f000, v130
	v_add_u32_e32 v193, 0x91c00, v130
	v_add_f32_e32 v178, 1.0, v178
	v_add_f32_e32 v179, 1.0, v179
	v_add_f32_e32 v180, 1.0, v180
	v_add_f32_e32 v181, 1.0, v181
	v_add_f32_e32 v182, 1.0, v182
; DI int TIDX() { int t = threadIdx.x; asm volatile("" : "+v"(t)); return t; }
; DI float sigmoidf_(float x) { return __builtin_amdgcn_rcpf(1.f + __expf(-x)); }
; DI void phase_ffn1(const P& p, int l, int hf, char* smem) {
;     ...
;     const int lane = TIDX() & 63, w = TIDX() >> 6, wm = w >> 1, wn = w & 1, hh = lane >> 5, c = lane & 31;
;     const int ml0 = m0 - mt0 * 128;
; #pragma unroll
;     for (int mi = 0; mi < 4; ++mi) {
;       const int rbase = ml0 + wm * 128 + mi * 32 + 4 * hh, n = c0 + wn * 32 + c;
; #pragma unroll
;       for (int i = 0; i < 16; ++i) {
;         const float g = acc[mi][0][i];
;         act[(size_t)EROW(rbase, i) * 2816 + n] = (h16)(g * sigmoidf_(g) * acc[mi][1][i]);
;       }
;     }
	v_add_f32_e32 v183, 1.0, v183
	v_add_f32_e32 v184, 1.0, v184
	v_add_f32_e32 v185, 1.0, v185
	v_rcp_f32_e32 v178, v178
	v_rcp_f32_e32 v179, v179
	v_rcp_f32_e32 v180, v180
	v_rcp_f32_e32 v181, v181
	v_rcp_f32_e32 v182, v182
	v_rcp_f32_e32 v183, v183
	v_rcp_f32_e32 v184, v184
	v_rcp_f32_e32 v185, v185
	v_mul_f32_e32 v178, v18, v178
	v_mul_f32_e32 v179, v19, v179
	v_mul_f32_e32 v180, v20, v180
	v_mul_f32_e32 v181, v21, v181
	v_mul_f32_e32 v182, v22, v182
	v_mul_f32_e32 v183, v23, v183
	v_mul_f32_e32 v184, v24, v184
	v_mul_f32_e32 v185, v25, v185
	v_fma_mixlo_f16 v178, v2, v178, 0
	v_fma_mixlo_f16 v180, v4, v180, 0
	v_fma_mixlo_f16 v182, v6, v182, 0
	v_fma_mixlo_f16 v184, v8, v184, 0
	v_fma_mixhi_f16 v178, v3, v179, 0
	v_fma_mixhi_f16 v180, v5, v181, 0
	v_fma_mixhi_f16 v182, v7, v183, 0
	v_fma_mixhi_f16 v184, v9, v185, 0
	v_mov_b32_dpp v186, v178 quad_perm:[1,0,3,2] row_mask:0xf bank_mask:0xf
	v_mov_b32_dpp v187, v180 quad_perm:[1,0,3,2] row_mask:0xf bank_mask:0xf
	v_mov_b32_dpp v188, v182 quad_perm:[1,0,3,2] row_mask:0xf bank_mask:0xf
	v_mov_b32_dpp v189, v184 quad_perm:[1,0,3,2] row_mask:0xf bank_mask:0xf
	v_perm_b32 v178, v186, v178, v194
	v_perm_b32 v180, v187, v180, v194
	v_perm_b32 v182, v188, v182, v194
	v_perm_b32 v184, v189, v184, v194
	global_store_dword v190, v178, s[8:9]
	global_store_dword v191, v180, s[8:9]
	global_store_dword v192, v182, s[8:9]
	global_store_dword v193, v184, s[8:9]
	v_mul_f32_e32 v178, 0xbfb8aa3b, v26
	v_mul_f32_e32 v179, 0xbfb8aa3b, v27
	v_mul_f32_e32 v180, 0xbfb8aa3b, v28
	v_mul_f32_e32 v181, 0xbfb8aa3b, v29
	v_mul_f32_e32 v182, 0xbfb8aa3b, v30
	v_mul_f32_e32 v183, 0xbfb8aa3b, v31
	v_mul_f32_e32 v184, 0xbfb8aa3b, v32
	v_mul_f32_e32 v185, 0xbfb8aa3b, v33
	v_exp_f32_e32 v178, v178
	v_exp_f32_e32 v179, v179
	v_exp_f32_e32 v180, v180
	v_exp_f32_e32 v181, v181
	v_exp_f32_e32 v182, v182
	v_exp_f32_e32 v183, v183
	v_exp_f32_e32 v184, v184
	v_exp_f32_e32 v185, v185
	v_add_u32_e32 v190, 0x9a000, v130
	v_add_u32_e32 v191, 0x9cc00, v130
	v_add_u32_e32 v192, 0xa5000, v130
	v_add_u32_e32 v193, 0xa7c00, v130
	v_add_f32_e32 v178, 1.0, v178
	v_add_f32_e32 v179, 1.0, v179
	v_add_f32_e32 v180, 1.0, v180
	v_add_f32_e32 v181, 1.0, v181
	v_add_f32_e32 v182, 1.0, v182
	v_add_f32_e32 v183, 1.0, v183
	v_add_f32_e32 v184, 1.0, v184
	v_add_f32_e32 v185, 1.0, v185
	v_rcp_f32_e32 v178, v178
	v_rcp_f32_e32 v179, v179
	v_rcp_f32_e32 v180, v180
	v_rcp_f32_e32 v181, v181
	v_rcp_f32_e32 v182, v182
	v_rcp_f32_e32 v183, v183
	v_rcp_f32_e32 v184, v184
	v_rcp_f32_e32 v185, v185
	v_mul_f32_e32 v178, v26, v178
	v_mul_f32_e32 v179, v27, v179
	v_mul_f32_e32 v180, v28, v180
	v_mul_f32_e32 v181, v29, v181
	v_mul_f32_e32 v182, v30, v182
	v_mul_f32_e32 v183, v31, v183
	v_mul_f32_e32 v184, v32, v184
	v_mul_f32_e32 v185, v33, v185
	v_fma_mixlo_f16 v178, v10, v178, 0
	v_fma_mixlo_f16 v180, v12, v180, 0
	v_fma_mixlo_f16 v182, v14, v182, 0
	v_fma_mixlo_f16 v184, v16, v184, 0
	v_fma_mixhi_f16 v178, v11, v179, 0
	v_fma_mixhi_f16 v180, v13, v181, 0
	v_fma_mixhi_f16 v182, v15, v183, 0
	v_fma_mixhi_f16 v184, v17, v185, 0
	v_mov_b32_dpp v186, v178 quad_perm:[1,0,3,2] row_mask:0xf bank_mask:0xf
	v_mov_b32_dpp v187, v180 quad_perm:[1,0,3,2] row_mask:0xf bank_mask:0xf
	v_mov_b32_dpp v188, v182 quad_perm:[1,0,3,2] row_mask:0xf bank_mask:0xf
	v_mov_b32_dpp v189, v184 quad_perm:[1,0,3,2] row_mask:0xf bank_mask:0xf
	v_perm_b32 v178, v186, v178, v194
	v_perm_b32 v180, v187, v180, v194
	v_perm_b32 v182, v188, v182, v194
	v_perm_b32 v184, v189, v184, v194
	global_store_dword v190, v178, s[8:9]
	global_store_dword v191, v180, s[8:9]
	global_store_dword v192, v182, s[8:9]
	global_store_dword v193, v184, s[8:9]
